# stack2 plus: K-slice residual epilogues (layer-0 ctx panels of w_out and ff2) issue their four gate-vector loads together instead of one behind each group of eight stores
# baseline (speedup 1.0000x reference)
; #define GAS __attribute__((address_space(1)))
;     __device__ __forceinline__ void operator()(const f32x4 (&acc)[2][2][4][2], const Unit& u, int wr, int wc, int fr, int fq) const {
;     ...
;         const int bslot = u.pm < 32 ? (u.pm >> 3) : 4;
;         const float* gp = gate + (size_t)bslot * MODW + col0;
;         if (u.ks >= 0) {
;             float* pp = part + ((size_t)u.ks * NCTX + (row0 - NLAT)) * DM + col0;
; #pragma unroll
;             for (int bj = 0; bj < 2; ++bj)
; #pragma unroll
;                 for (int n = 0; n < 2; ++n) { const f32x4 gv = *(const GAS f32x4*)(gp + bj * HALF + n * 16);
.LBB0_127:
	s_and_b64 vcc, exec, s[26:27]
	s_cbranch_vccz .LBB0_126
	global_load_dwordx4 v[142:145], v[136:137], off
	global_load_dwordx4 v[178:181], v[136:137], off offset:64
	global_load_dwordx4 v[182:185], v[136:137], off offset:512
	global_load_dwordx4 v[186:189], v[136:137], off offset:576
	s_mov_b32 s25, s37
	s_lshl_b64 s[24:25], s[24:25], 23
	v_ashrrev_i32_e32 v141, 31, v140
	s_add_u32 s24, s82, s24
	v_lshlrev_b64 v[140:141], 13, v[140:141]
	s_addc_u32 s25, s83, s25
	v_lshl_add_u64 v[140:141], s[24:25], 0, v[140:141]
	v_lshl_add_u64 v[140:141], v[138:139], 2, v[140:141]
	s_brev_b32 s17, 63
	v_add_co_u32_e32 v146, vcc, s17, v140
	s_mov_b32 s17, 0xfc020000
	s_nop 0
	v_addc_co_u32_e32 v147, vcc, -1, v141, vcc
	s_brev_b32 s24, 63
	s_mov_b32 s25, -1
	v_lshl_add_u64 v[138:139], v[140:141], 0, s[24:25]
	s_waitcnt vmcnt(0)
; #define GAS __attribute__((address_space(1)))
;     __device__ __forceinline__ void operator()(const f32x4 (&acc)[2][2][4][2], const Unit& u, int wr, int wc, int fr, int fq) const {
;     ...
;         if (u.ks >= 0) {
;             float* pp = part + ((size_t)u.ks * NCTX + (row0 - NLAT)) * DM + col0;
; #pragma unroll
;             for (int bj = 0; bj < 2; ++bj)
; #pragma unroll
;                 for (int n = 0; n < 2; ++n) { const f32x4 gv = *(const GAS f32x4*)(gp + bj * HALF + n * 16);
; #pragma unroll
;                     for (int ai = 0; ai < 2; ++ai)
; #pragma unroll
;                         for (int m = 0; m < 4; ++m) *(GAS f32x4*)(pp + (size_t)(ai * HALF + m * 16) * DM + bj * HALF + n * 16) = gv * acc[ai][bj][m][n]; }
;             return;
	v_pk_mul_f32 v[128:129], v[128:129], v[144:145]
	v_pk_mul_f32 v[126:127], v[126:127], v[142:143]
	global_store_dwordx4 v[146:147], v[126:129], off
	v_pk_mul_f32 v[124:125], v[124:125], v[144:145]
	v_pk_mul_f32 v[122:123], v[122:123], v[142:143]
	v_add_co_u32_e32 v126, vcc, s17, v140
	s_mov_b32 s17, 0xfc040000
	s_nop 0
	v_addc_co_u32_e32 v127, vcc, -1, v141, vcc
	global_store_dwordx4 v[126:127], v[122:125], off
	v_pk_mul_f32 v[120:121], v[120:121], v[144:145]
	v_pk_mul_f32 v[118:119], v[118:119], v[142:143]
	v_add_co_u32_e32 v122, vcc, s17, v140
	s_mov_b32 s17, 0xfc060000
	s_nop 0
	v_addc_co_u32_e32 v123, vcc, -1, v141, vcc
	global_store_dwordx4 v[122:123], v[118:121], off
	v_pk_mul_f32 v[116:117], v[116:117], v[144:145]
	v_pk_mul_f32 v[114:115], v[114:115], v[142:143]
	v_add_co_u32_e32 v118, vcc, s17, v140
	s_mov_b32 s17, 0xfc100000
	s_nop 0
	v_addc_co_u32_e32 v119, vcc, -1, v141, vcc
	global_store_dwordx4 v[118:119], v[114:117], off
	v_pk_mul_f32 v[112:113], v[112:113], v[144:145]
	v_pk_mul_f32 v[110:111], v[110:111], v[142:143]
	v_add_co_u32_e32 v114, vcc, s17, v140
	s_mov_b32 s17, 0xfc120000
	s_nop 0
	v_addc_co_u32_e32 v115, vcc, -1, v141, vcc
	global_store_dwordx4 v[114:115], v[110:113], off
	v_pk_mul_f32 v[108:109], v[108:109], v[144:145]
	v_pk_mul_f32 v[106:107], v[106:107], v[142:143]
	v_add_co_u32_e32 v110, vcc, s17, v140
	s_mov_b32 s17, 0xfc140000
	s_nop 0
	v_addc_co_u32_e32 v111, vcc, -1, v141, vcc
	global_store_dwordx4 v[110:111], v[106:109], off
	v_pk_mul_f32 v[104:105], v[104:105], v[144:145]
	v_pk_mul_f32 v[102:103], v[102:103], v[142:143]
	v_add_co_u32_e32 v106, vcc, s17, v140
	s_mov_b32 s17, 0xfc160000
	s_nop 0
	v_addc_co_u32_e32 v107, vcc, -1, v141, vcc
	global_store_dwordx4 v[106:107], v[102:105], off
	v_pk_mul_f32 v[100:101], v[100:101], v[144:145]
	v_pk_mul_f32 v[98:99], v[98:99], v[142:143]
	v_add_co_u32_e32 v102, vcc, s17, v140
	s_mov_b32 s17, 0xfc021000
	s_nop 0
	v_addc_co_u32_e32 v103, vcc, -1, v141, vcc
	global_store_dwordx4 v[102:103], v[98:101], off
	v_pk_mul_f32 v[96:97], v[96:97], v[180:181]
	v_pk_mul_f32 v[94:95], v[94:95], v[178:179]
	global_store_dwordx4 v[138:139], v[94:97], off offset:64
	s_nop 1
	v_pk_mul_f32 v[94:95], v[92:93], v[180:181]
	v_pk_mul_f32 v[92:93], v[90:91], v[178:179]
	v_add_co_u32_e32 v90, vcc, s17, v140
	s_mov_b32 s17, 0xfc041000
	s_nop 0
	v_addc_co_u32_e32 v91, vcc, -1, v141, vcc
	global_store_dwordx4 v[90:91], v[92:95], off offset:-4032
	s_nop 1
	v_pk_mul_f32 v[92:93], v[86:87], v[178:179]
	v_add_co_u32_e32 v86, vcc, s17, v140
	v_pk_mul_f32 v[94:95], v[88:89], v[180:181]
	s_nop 0
	v_addc_co_u32_e32 v87, vcc, -1, v141, vcc
	s_mov_b32 s17, 0xfc061000
	global_store_dwordx4 v[86:87], v[92:95], off offset:-4032
	s_nop 1
	v_pk_mul_f32 v[92:93], v[82:83], v[178:179]
	v_add_co_u32_e32 v82, vcc, s17, v140
	v_pk_mul_f32 v[94:95], v[84:85], v[180:181]
	s_nop 0
	v_addc_co_u32_e32 v83, vcc, -1, v141, vcc
	s_mov_b32 s17, 0xfc101000
	global_store_dwordx4 v[82:83], v[92:95], off offset:-4032
	s_nop 1
	v_pk_mul_f32 v[92:93], v[78:79], v[178:179]
	v_add_co_u32_e32 v78, vcc, s17, v140
	v_pk_mul_f32 v[94:95], v[80:81], v[180:181]
	s_nop 0
	v_addc_co_u32_e32 v79, vcc, -1, v141, vcc
	s_mov_b32 s17, 0xfc121000
	global_store_dwordx4 v[78:79], v[92:95], off offset:-4032
	s_nop 1
	v_pk_mul_f32 v[92:93], v[74:75], v[178:179]
	v_add_co_u32_e32 v74, vcc, s17, v140
	v_pk_mul_f32 v[94:95], v[76:77], v[180:181]
	s_nop 0
	v_addc_co_u32_e32 v75, vcc, -1, v141, vcc
	s_mov_b32 s17, 0xfc141000
	global_store_dwordx4 v[74:75], v[92:95], off offset:-4032
	s_nop 1
	v_pk_mul_f32 v[92:93], v[70:71], v[178:179]
	v_add_co_u32_e32 v70, vcc, s17, v140
	v_pk_mul_f32 v[94:95], v[72:73], v[180:181]
	s_nop 0
	v_addc_co_u32_e32 v71, vcc, -1, v141, vcc
	s_mov_b32 s17, 0xfc161000
	global_store_dwordx4 v[70:71], v[92:95], off offset:-4032
	s_nop 1
	v_pk_mul_f32 v[92:93], v[66:67], v[178:179]
	v_add_co_u32_e32 v66, vcc, s17, v140
	v_pk_mul_f32 v[94:95], v[68:69], v[180:181]
	s_nop 0
	v_addc_co_u32_e32 v67, vcc, -1, v141, vcc
	global_store_dwordx4 v[66:67], v[92:95], off offset:-4032
	v_pk_mul_f32 v[64:65], v[64:65], v[184:185]
	v_pk_mul_f32 v[62:63], v[62:63], v[182:183]
	v_pk_mul_f32 v[60:61], v[60:61], v[184:185]
	v_pk_mul_f32 v[58:59], v[58:59], v[182:183]
	v_pk_mul_f32 v[56:57], v[56:57], v[184:185]
	v_pk_mul_f32 v[54:55], v[54:55], v[182:183]
	v_pk_mul_f32 v[52:53], v[52:53], v[184:185]
	v_pk_mul_f32 v[50:51], v[50:51], v[182:183]
	v_pk_mul_f32 v[48:49], v[48:49], v[184:185]
	v_pk_mul_f32 v[46:47], v[46:47], v[182:183]
	v_pk_mul_f32 v[44:45], v[44:45], v[184:185]
	v_pk_mul_f32 v[42:43], v[42:43], v[182:183]
	v_pk_mul_f32 v[36:37], v[36:37], v[184:185]
	v_pk_mul_f32 v[34:35], v[34:35], v[182:183]
	v_pk_mul_f32 v[28:29], v[28:29], v[184:185]
	v_pk_mul_f32 v[26:27], v[26:27], v[182:183]
	global_store_dwordx4 v[138:139], v[62:65], off offset:512
	global_store_dwordx4 v[90:91], v[58:61], off offset:-3584
	global_store_dwordx4 v[86:87], v[54:57], off offset:-3584
	global_store_dwordx4 v[82:83], v[50:53], off offset:-3584
	global_store_dwordx4 v[78:79], v[46:49], off offset:-3584
	global_store_dwordx4 v[74:75], v[42:45], off offset:-3584
	global_store_dwordx4 v[70:71], v[34:37], off offset:-3584
	global_store_dwordx4 v[66:67], v[26:29], off offset:-3584
	v_pk_mul_f32 v[36:37], v[40:41], v[188:189]
	v_pk_mul_f32 v[34:35], v[38:39], v[186:187]
	v_pk_mul_f32 v[32:33], v[32:33], v[188:189]
	v_pk_mul_f32 v[30:31], v[30:31], v[186:187]
	v_pk_mul_f32 v[24:25], v[24:25], v[188:189]
	v_pk_mul_f32 v[22:23], v[22:23], v[186:187]
	v_pk_mul_f32 v[20:21], v[20:21], v[188:189]
	v_pk_mul_f32 v[18:19], v[18:19], v[186:187]
	v_pk_mul_f32 v[16:17], v[16:17], v[188:189]
	v_pk_mul_f32 v[14:15], v[14:15], v[186:187]
	v_pk_mul_f32 v[12:13], v[12:13], v[188:189]
	v_pk_mul_f32 v[10:11], v[10:11], v[186:187]
	v_pk_mul_f32 v[8:9], v[8:9], v[188:189]
	v_pk_mul_f32 v[6:7], v[6:7], v[186:187]
	v_pk_mul_f32 v[4:5], v[4:5], v[188:189]
	v_pk_mul_f32 v[2:3], v[2:3], v[186:187]
	global_store_dwordx4 v[138:139], v[34:37], off offset:576
	global_store_dwordx4 v[90:91], v[30:33], off offset:-3520
	global_store_dwordx4 v[86:87], v[22:25], off offset:-3520
	global_store_dwordx4 v[82:83], v[18:21], off offset:-3520
	global_store_dwordx4 v[78:79], v[14:17], off offset:-3520
	global_store_dwordx4 v[74:75], v[10:13], off offset:-3520
	global_store_dwordx4 v[70:71], v[6:9], off offset:-3520
	global_store_dwordx4 v[66:67], v[2:5], off offset:-3520
	s_and_b64 vcc, exec, s[0:1]
	s_mov_b64 s[0:1], -1
	s_cbranch_vccnz .LBB0_95

; #define GAS __attribute__((address_space(1)))
;     __device__ __forceinline__ void operator()(const f32x4 (&acc)[2][2][4][2], const Unit& u, int wr, int wc, int fr, int fq) const {
;     ...
;         const int bslot = u.pm < 32 ? (u.pm >> 3) : 4;
;         const float* gp = gate + (size_t)bslot * MODW + col0;
;         if (u.ks >= 0) {
;             float* pp = part + ((size_t)u.ks * NCTX + (row0 - NLAT)) * DM + col0;
; #pragma unroll
;             for (int bj = 0; bj < 2; ++bj)
; #pragma unroll
;                 for (int n = 0; n < 2; ++n) { const f32x4 gv = *(const GAS f32x4*)(gp + bj * HALF + n * 16);
.LBB0_221:
	s_and_b64 vcc, exec, s[26:27]
	s_cbranch_vccz .LBB0_220
	global_load_dwordx4 v[142:145], v[136:137], off
	global_load_dwordx4 v[178:181], v[136:137], off offset:64
	global_load_dwordx4 v[182:185], v[136:137], off offset:512
	global_load_dwordx4 v[186:189], v[136:137], off offset:576
	s_lshl_b64 s[26:27], s[36:37], 23
	v_ashrrev_i32_e32 v141, 31, v140
	s_add_u32 s26, s82, s26
	v_lshlrev_b64 v[140:141], 13, v[140:141]
	s_addc_u32 s27, s83, s27
	v_lshl_add_u64 v[140:141], s[26:27], 0, v[140:141]
	v_lshl_add_u64 v[140:141], v[138:139], 2, v[140:141]
	s_brev_b32 s19, 63
	v_add_co_u32_e32 v146, vcc, s19, v140
	s_mov_b32 s19, 0xfc020000
	s_nop 0
	v_addc_co_u32_e32 v147, vcc, -1, v141, vcc
	s_brev_b32 s26, 63
	s_mov_b32 s27, -1
	v_lshl_add_u64 v[138:139], v[140:141], 0, s[26:27]
	s_waitcnt vmcnt(0)
; #define GAS __attribute__((address_space(1)))
;     __device__ __forceinline__ void operator()(const f32x4 (&acc)[2][2][4][2], const Unit& u, int wr, int wc, int fr, int fq) const {
;     ...
;         if (u.ks >= 0) {
;             float* pp = part + ((size_t)u.ks * NCTX + (row0 - NLAT)) * DM + col0;
; #pragma unroll
;             for (int bj = 0; bj < 2; ++bj)
; #pragma unroll
;                 for (int n = 0; n < 2; ++n) { const f32x4 gv = *(const GAS f32x4*)(gp + bj * HALF + n * 16);
; #pragma unroll
;                     for (int ai = 0; ai < 2; ++ai)
; #pragma unroll
;                         for (int m = 0; m < 4; ++m) *(GAS f32x4*)(pp + (size_t)(ai * HALF + m * 16) * DM + bj * HALF + n * 16) = gv * acc[ai][bj][m][n]; }
;             return;
	v_pk_mul_f32 v[128:129], v[128:129], v[144:145]
	v_pk_mul_f32 v[126:127], v[126:127], v[142:143]
	global_store_dwordx4 v[146:147], v[126:129], off
	v_pk_mul_f32 v[124:125], v[124:125], v[144:145]
	v_pk_mul_f32 v[122:123], v[122:123], v[142:143]
	v_add_co_u32_e32 v126, vcc, s19, v140
	s_mov_b32 s19, 0xfc040000
	s_nop 0
	v_addc_co_u32_e32 v127, vcc, -1, v141, vcc
	global_store_dwordx4 v[126:127], v[122:125], off
	v_pk_mul_f32 v[120:121], v[120:121], v[144:145]
	v_pk_mul_f32 v[118:119], v[118:119], v[142:143]
	v_add_co_u32_e32 v122, vcc, s19, v140
	s_mov_b32 s19, 0xfc060000
	s_nop 0
	v_addc_co_u32_e32 v123, vcc, -1, v141, vcc
	global_store_dwordx4 v[122:123], v[118:121], off
	v_pk_mul_f32 v[116:117], v[116:117], v[144:145]
	v_pk_mul_f32 v[114:115], v[114:115], v[142:143]
	v_add_co_u32_e32 v118, vcc, s19, v140
	s_mov_b32 s19, 0xfc100000
	s_nop 0
	v_addc_co_u32_e32 v119, vcc, -1, v141, vcc
	global_store_dwordx4 v[118:119], v[114:117], off
	v_pk_mul_f32 v[112:113], v[112:113], v[144:145]
	v_pk_mul_f32 v[110:111], v[110:111], v[142:143]
	v_add_co_u32_e32 v114, vcc, s19, v140
	s_mov_b32 s19, 0xfc120000
	s_nop 0
	v_addc_co_u32_e32 v115, vcc, -1, v141, vcc
	global_store_dwordx4 v[114:115], v[110:113], off
	v_pk_mul_f32 v[108:109], v[108:109], v[144:145]
	v_pk_mul_f32 v[106:107], v[106:107], v[142:143]
	v_add_co_u32_e32 v110, vcc, s19, v140
	s_mov_b32 s19, 0xfc140000
	s_nop 0
	v_addc_co_u32_e32 v111, vcc, -1, v141, vcc
	global_store_dwordx4 v[110:111], v[106:109], off
	v_pk_mul_f32 v[104:105], v[104:105], v[144:145]
	v_pk_mul_f32 v[102:103], v[102:103], v[142:143]
	v_add_co_u32_e32 v106, vcc, s19, v140
	s_mov_b32 s19, 0xfc160000
	s_nop 0
	v_addc_co_u32_e32 v107, vcc, -1, v141, vcc
	global_store_dwordx4 v[106:107], v[102:105], off
	v_pk_mul_f32 v[100:101], v[100:101], v[144:145]
	v_pk_mul_f32 v[98:99], v[98:99], v[142:143]
	v_add_co_u32_e32 v102, vcc, s19, v140
	s_mov_b32 s19, 0xfc021000
	s_nop 0
	v_addc_co_u32_e32 v103, vcc, -1, v141, vcc
	global_store_dwordx4 v[102:103], v[98:101], off
	v_pk_mul_f32 v[96:97], v[96:97], v[180:181]
	v_pk_mul_f32 v[94:95], v[94:95], v[178:179]
	global_store_dwordx4 v[138:139], v[94:97], off offset:64
	s_nop 1
	v_pk_mul_f32 v[94:95], v[92:93], v[180:181]
	v_pk_mul_f32 v[92:93], v[90:91], v[178:179]
	v_add_co_u32_e32 v90, vcc, s19, v140
	s_mov_b32 s19, 0xfc041000
	s_nop 0
	v_addc_co_u32_e32 v91, vcc, -1, v141, vcc
	global_store_dwordx4 v[90:91], v[92:95], off offset:-4032
	s_nop 1
	v_pk_mul_f32 v[92:93], v[86:87], v[178:179]
	v_add_co_u32_e32 v86, vcc, s19, v140
	v_pk_mul_f32 v[94:95], v[88:89], v[180:181]
	s_nop 0
	v_addc_co_u32_e32 v87, vcc, -1, v141, vcc
	s_mov_b32 s19, 0xfc061000
	global_store_dwordx4 v[86:87], v[92:95], off offset:-4032
	s_nop 1
	v_pk_mul_f32 v[92:93], v[82:83], v[178:179]
	v_add_co_u32_e32 v82, vcc, s19, v140
	v_pk_mul_f32 v[94:95], v[84:85], v[180:181]
	s_nop 0
	v_addc_co_u32_e32 v83, vcc, -1, v141, vcc
	s_mov_b32 s19, 0xfc101000
	global_store_dwordx4 v[82:83], v[92:95], off offset:-4032
	s_nop 1
	v_pk_mul_f32 v[92:93], v[78:79], v[178:179]
	v_add_co_u32_e32 v78, vcc, s19, v140
	v_pk_mul_f32 v[94:95], v[80:81], v[180:181]
	s_nop 0
	v_addc_co_u32_e32 v79, vcc, -1, v141, vcc
	s_mov_b32 s19, 0xfc121000
	global_store_dwordx4 v[78:79], v[92:95], off offset:-4032
	s_nop 1
	v_pk_mul_f32 v[92:93], v[74:75], v[178:179]
	v_add_co_u32_e32 v74, vcc, s19, v140
	v_pk_mul_f32 v[94:95], v[76:77], v[180:181]
	s_nop 0
	v_addc_co_u32_e32 v75, vcc, -1, v141, vcc
	s_mov_b32 s19, 0xfc141000
	global_store_dwordx4 v[74:75], v[92:95], off offset:-4032
	s_nop 1
	v_pk_mul_f32 v[92:93], v[70:71], v[178:179]
	v_add_co_u32_e32 v70, vcc, s19, v140
	v_pk_mul_f32 v[94:95], v[72:73], v[180:181]
	s_nop 0
	v_addc_co_u32_e32 v71, vcc, -1, v141, vcc
	s_mov_b32 s19, 0xfc161000
	global_store_dwordx4 v[70:71], v[92:95], off offset:-4032
	s_nop 1
	v_pk_mul_f32 v[92:93], v[66:67], v[178:179]
	v_add_co_u32_e32 v66, vcc, s19, v140
	v_pk_mul_f32 v[94:95], v[68:69], v[180:181]
	s_nop 0
	v_addc_co_u32_e32 v67, vcc, -1, v141, vcc
	global_store_dwordx4 v[66:67], v[92:95], off offset:-4032
	v_pk_mul_f32 v[64:65], v[64:65], v[184:185]
	v_pk_mul_f32 v[62:63], v[62:63], v[182:183]
	v_pk_mul_f32 v[60:61], v[60:61], v[184:185]
	v_pk_mul_f32 v[58:59], v[58:59], v[182:183]
	v_pk_mul_f32 v[56:57], v[56:57], v[184:185]
	v_pk_mul_f32 v[54:55], v[54:55], v[182:183]
	v_pk_mul_f32 v[52:53], v[52:53], v[184:185]
	v_pk_mul_f32 v[50:51], v[50:51], v[182:183]
	v_pk_mul_f32 v[48:49], v[48:49], v[184:185]
	v_pk_mul_f32 v[46:47], v[46:47], v[182:183]
	v_pk_mul_f32 v[40:41], v[40:41], v[184:185]
	v_pk_mul_f32 v[38:39], v[38:39], v[182:183]
	v_pk_mul_f32 v[32:33], v[32:33], v[184:185]
	v_pk_mul_f32 v[30:31], v[30:31], v[182:183]
	v_pk_mul_f32 v[24:25], v[24:25], v[184:185]
	v_pk_mul_f32 v[22:23], v[22:23], v[182:183]
	global_store_dwordx4 v[138:139], v[62:65], off offset:512
	global_store_dwordx4 v[90:91], v[58:61], off offset:-3584
	global_store_dwordx4 v[86:87], v[54:57], off offset:-3584
	global_store_dwordx4 v[82:83], v[50:53], off offset:-3584
	global_store_dwordx4 v[78:79], v[46:49], off offset:-3584
	global_store_dwordx4 v[74:75], v[38:41], off offset:-3584
	global_store_dwordx4 v[70:71], v[30:33], off offset:-3584
	global_store_dwordx4 v[66:67], v[22:25], off offset:-3584
	v_pk_mul_f32 v[32:33], v[44:45], v[188:189]
	v_pk_mul_f32 v[30:31], v[42:43], v[186:187]
	global_store_dwordx4 v[138:139], v[30:33], off offset:576
	v_pk_mul_f32 v[28:29], v[28:29], v[188:189]
	v_pk_mul_f32 v[26:27], v[26:27], v[186:187]
	v_pk_mul_f32 v[32:33], v[36:37], v[188:189]
	v_pk_mul_f32 v[30:31], v[34:35], v[186:187]
	v_pk_mul_f32 v[20:21], v[20:21], v[188:189]
	v_pk_mul_f32 v[18:19], v[18:19], v[186:187]
	v_pk_mul_f32 v[16:17], v[16:17], v[188:189]
	v_pk_mul_f32 v[14:15], v[14:15], v[186:187]
	v_pk_mul_f32 v[12:13], v[12:13], v[188:189]
	v_pk_mul_f32 v[10:11], v[10:11], v[186:187]
	v_pk_mul_f32 v[8:9], v[8:9], v[188:189]
	v_pk_mul_f32 v[6:7], v[6:7], v[186:187]
	v_pk_mul_f32 v[4:5], v[4:5], v[188:189]
	v_pk_mul_f32 v[2:3], v[2:3], v[186:187]
	global_store_dwordx4 v[90:91], v[30:33], off offset:-3520
	global_store_dwordx4 v[86:87], v[26:29], off offset:-3520
	global_store_dwordx4 v[82:83], v[18:21], off offset:-3520
	global_store_dwordx4 v[78:79], v[14:17], off offset:-3520
	global_store_dwordx4 v[74:75], v[10:13], off offset:-3520
	global_store_dwordx4 v[70:71], v[6:9], off offset:-3520
	global_store_dwordx4 v[66:67], v[2:5], off offset:-3520
	s_and_b64 vcc, exec, s[4:5]
	s_mov_b64 s[4:5], -1
	s_cbranch_vccnz .LBB0_188
